# placement guard strengthened: the eight populated XCCs must carry eight different single blockIdx%8 group bits (else global barriers)
# speedup vs baseline: 1.0381x; 1.0006x over previous
.LBB0_357:
	s_or_b64 exec, exec, s[4:5]
	s_and_saveexec_b64 s[4:5], s[6:7]
	s_cbranch_execz .LBB0_359
	s_add_u32 s12, s66, 0x800
	s_addc_u32 s13, s67, 0
	v_mov_b32_e32 v12, 0
	v_mov_b32_e32 v14, 0
	v_mov_b32_e32 v15, 0
	global_load_dword v4, v1, s[12:13] offset:-1536 sc1
	global_load_dword v5, v1, s[12:13] offset:-1280 sc1
	global_load_dword v6, v1, s[12:13] offset:-1024 sc1
	global_load_dword v7, v1, s[12:13] offset:-768 sc1
	global_load_dword v8, v1, s[12:13] offset:-512 sc1
	global_load_dword v9, v1, s[12:13] offset:-256 sc1
	global_load_dword v10, v1, s[12:13] offset:0 sc1
	global_load_dword v11, v1, s[12:13] offset:256 sc1
	s_waitcnt vmcnt(0)
	v_or_b32_e32 v12, v12, v4
	v_or_b32_e32 v12, v12, v5
	v_or_b32_e32 v12, v12, v6
	v_or_b32_e32 v12, v12, v7
	v_or_b32_e32 v12, v12, v8
	v_or_b32_e32 v12, v12, v9
	v_or_b32_e32 v12, v12, v10
	v_or_b32_e32 v12, v12, v11
	global_load_dword v4, v1, s[12:13] offset:512 sc1
	global_load_dword v5, v1, s[12:13] offset:768 sc1
	global_load_dword v6, v1, s[12:13] offset:1024 sc1
	global_load_dword v7, v1, s[12:13] offset:1280 sc1
	global_load_dword v8, v1, s[12:13] offset:1536 sc1
	global_load_dword v9, v1, s[12:13] offset:1792 sc1
	global_load_dword v10, v1, s[12:13] offset:2048 sc1
	global_load_dword v11, v1, s[12:13] offset:2304 sc1
	s_waitcnt vmcnt(0)
	v_or_b32_e32 v12, v12, v4
	v_or_b32_e32 v12, v12, v5
	v_or_b32_e32 v12, v12, v6
	v_or_b32_e32 v12, v12, v7
	v_or_b32_e32 v12, v12, v8
	v_or_b32_e32 v12, v12, v9
	v_or_b32_e32 v12, v12, v10
	v_or_b32_e32 v12, v12, v11
	global_load_dword v4, v1, s[12:13] offset:-1408 sc1
	global_load_dword v5, v1, s[12:13] offset:-1152 sc1
	global_load_dword v6, v1, s[12:13] offset:-896 sc1
	global_load_dword v7, v1, s[12:13] offset:-640 sc1
	global_load_dword v8, v1, s[12:13] offset:-384 sc1
	global_load_dword v9, v1, s[12:13] offset:-128 sc1
	global_load_dword v10, v1, s[12:13] offset:128 sc1
	global_load_dword v11, v1, s[12:13] offset:384 sc1
	s_waitcnt vmcnt(0)
	v_add_u32_e32 v13, -1, v4
	v_and_b32_e32 v13, v13, v4
	v_or_b32_e32 v14, v14, v13
	v_or_b32_e32 v15, v15, v4
	v_add_u32_e32 v13, -1, v5
	v_and_b32_e32 v13, v13, v5
	v_or_b32_e32 v14, v14, v13
	v_or_b32_e32 v15, v15, v5
	v_add_u32_e32 v13, -1, v6
	v_and_b32_e32 v13, v13, v6
	v_or_b32_e32 v14, v14, v13
	v_or_b32_e32 v15, v15, v6
	v_add_u32_e32 v13, -1, v7
	v_and_b32_e32 v13, v13, v7
	v_or_b32_e32 v14, v14, v13
	v_or_b32_e32 v15, v15, v7
	v_add_u32_e32 v13, -1, v8
	v_and_b32_e32 v13, v13, v8
	v_or_b32_e32 v14, v14, v13
	v_or_b32_e32 v15, v15, v8
	v_add_u32_e32 v13, -1, v9
	v_and_b32_e32 v13, v13, v9
	v_or_b32_e32 v14, v14, v13
	v_or_b32_e32 v15, v15, v9
	v_add_u32_e32 v13, -1, v10
	v_and_b32_e32 v13, v13, v10
	v_or_b32_e32 v14, v14, v13
	v_or_b32_e32 v15, v15, v10
	v_add_u32_e32 v13, -1, v11
	v_and_b32_e32 v13, v13, v11
	v_or_b32_e32 v14, v14, v13
	v_or_b32_e32 v15, v15, v11
	global_load_dword v4, v1, s[12:13] offset:640 sc1
	global_load_dword v5, v1, s[12:13] offset:896 sc1
	global_load_dword v6, v1, s[12:13] offset:1152 sc1
	global_load_dword v7, v1, s[12:13] offset:1408 sc1
	global_load_dword v8, v1, s[12:13] offset:1664 sc1
	global_load_dword v9, v1, s[12:13] offset:1920 sc1
	global_load_dword v10, v1, s[12:13] offset:2176 sc1
	global_load_dword v11, v1, s[12:13] offset:2432 sc1
	s_waitcnt vmcnt(0)
	v_add_u32_e32 v13, -1, v4
	v_and_b32_e32 v13, v13, v4
	v_or_b32_e32 v14, v14, v13
	v_or_b32_e32 v15, v15, v4
	v_add_u32_e32 v13, -1, v5
	v_and_b32_e32 v13, v13, v5
	v_or_b32_e32 v14, v14, v13
	v_or_b32_e32 v15, v15, v5
	v_add_u32_e32 v13, -1, v6
	v_and_b32_e32 v13, v13, v6
	v_or_b32_e32 v14, v14, v13
	v_or_b32_e32 v15, v15, v6
	v_add_u32_e32 v13, -1, v7
	v_and_b32_e32 v13, v13, v7
	v_or_b32_e32 v14, v14, v13
	v_or_b32_e32 v15, v15, v7
	v_add_u32_e32 v13, -1, v8
	v_and_b32_e32 v13, v13, v8
	v_or_b32_e32 v14, v14, v13
	v_or_b32_e32 v15, v15, v8
	v_add_u32_e32 v13, -1, v9
	v_and_b32_e32 v13, v13, v9
	v_or_b32_e32 v14, v14, v13
	v_or_b32_e32 v15, v15, v9
	v_add_u32_e32 v13, -1, v10
	v_and_b32_e32 v13, v13, v10
	v_or_b32_e32 v14, v14, v13
	v_or_b32_e32 v15, v15, v10
	v_add_u32_e32 v13, -1, v11
	v_and_b32_e32 v13, v13, v11
	v_or_b32_e32 v14, v14, v13
	v_or_b32_e32 v15, v15, v11
	v_cmp_eq_u32_e32 vcc, 32, v12
	v_cmp_eq_u32_e64 s[14:15], 0, v14
	s_and_b64 vcc, vcc, s[14:15]
	v_mov_b32_e32 v13, 0xff
	v_cmp_eq_u32_e64 s[14:15], v13, v15
	s_and_b64 vcc, vcc, s[14:15]
	s_nop 1
	v_cndmask_b32_e64 v12, 2, 1, vcc
	v_add_co_u32_e32 v4, vcc, 0xffffef00, v2
	s_nop 1
	v_addc_co_u32_e32 v5, vcc, -1, v3, vcc
	global_atomic_add v[4:5], v12, off offset:4
	global_atomic_add v[4:5], v12, off offset:260
	global_atomic_add v[4:5], v12, off offset:516
	global_atomic_add v[4:5], v12, off offset:772
	global_atomic_add v[4:5], v12, off offset:1028
	global_atomic_add v[4:5], v12, off offset:1284
	global_atomic_add v[4:5], v12, off offset:1540
	global_atomic_add v[4:5], v12, off offset:1796
	global_atomic_add v[4:5], v12, off offset:2052
	global_atomic_add v[4:5], v12, off offset:2308
	global_atomic_add v[4:5], v12, off offset:2564
	global_atomic_add v[4:5], v12, off offset:2820
	global_atomic_add v[4:5], v12, off offset:3076
	global_atomic_add v[4:5], v12, off offset:3332
	global_atomic_add v[4:5], v12, off offset:3588
	global_atomic_add v[4:5], v12, off offset:3844
	s_waitcnt vmcnt(0)
	v_mov_b32_e32 v0, 1
	global_atomic_add v[2:3], v0, off
	v_add_co_u32_e32 v2, vcc, 0xffffef00, v2
	s_nop 1
	v_addc_co_u32_e32 v3, vcc, -1, v3, vcc
	global_atomic_add v[2:3], v0, off
	global_atomic_add v[2:3], v0, off offset:256
	global_atomic_add v[2:3], v0, off offset:512
	global_atomic_add v[2:3], v0, off offset:768
	global_atomic_add v[2:3], v0, off offset:1024
	global_atomic_add v[2:3], v0, off offset:1280
	global_atomic_add v[2:3], v0, off offset:1536
	global_atomic_add v[2:3], v0, off offset:1792
	global_atomic_add v[2:3], v0, off offset:2048
	global_atomic_add v[2:3], v0, off offset:2304
	global_atomic_add v[2:3], v0, off offset:2560
	global_atomic_add v[2:3], v0, off offset:2816
	global_atomic_add v[2:3], v0, off offset:3072
	global_atomic_add v[2:3], v0, off offset:3328
	global_atomic_add v[2:3], v0, off offset:3584
	global_atomic_add v[2:3], v0, off offset:3840
